# code placement: the latch + tile-head region of the second ffn_up tile loop moved by 32 bytes (unreachable pad, compensated in front of the K loop so that nothing else moves)
# speedup vs baseline: 1.0017x; 1.0017x over previous
; #define PG8_STAGE(bufoff, gbase, voff) do { _Pragma("unroll") for (int _i = 0; _i < 2; ++_i) \
;         __builtin_amdgcn_global_load_lds((const unsigned*)((const char*)(gbase) + (voff)[_i]), (LAS unsigned*)(lds + (bufoff) + ldsw + _i * 8192), 16, 0, 0); } while (0)
; #define PG8_WAIT_V(n) asm volatile("s_waitcnt vmcnt(" #n ")" ::: "memory")
; #define PG8_BAR __builtin_amdgcn_s_barrier()
; template <class Epi>
; __device__ __forceinline__ void gemm_phase(LAS unsigned char* lds, const Gemm g, const StaticOrder& S, const Epi& E) {
;     ...
;     for (int i = 0; i < 2; ++i) { int R, C; stage_rc(tid * 16 + i * 8192, R, C); const int Rb = Epi::PERM ? ((R & ~31) + perm32(R & 31)) : R;
;         voffA[i] = (unsigned)(R * g.lda + C) * 2u; voffB[i] = (unsigned)(Rb * K + C) * 2u; }
;     const size_t kstep = (size_t)(BK * 2);
;     const size_t hstepA = (size_t)HALF * g.lda * 2, hstepB = (size_t)HALF * K * 2;
;     const size_t rstepA = (size_t)g.lda * 2, tstepB = 2 * hstepB;
;     const size_t gstepA = g.grouped ? (size_t)K * 2 : 0;
;     const unsigned ldsw = (unsigned)wid * 1024u;
;     const int aoff = lds_byte(wr * 64 + fr, fq * 8), boff = lds_byte(wc * 32 + fr, fq * 8);
;     ...
;     Unit cur, nxt; int ui = 0;
;     if (!S.next(0, cur)) return;
;     f32x4 acc[2][2][4][2];
; #pragma unroll
;     for (int a = 0; a < 2; ++a)
; #pragma unroll
;         for (int b = 0; b < 2; ++b)
; #pragma unroll
;             for (int m = 0; m < 4; ++m)
; #pragma unroll
;                 for (int n = 0; n < 2; ++n) acc[a][b][m][n] = (f32x4){0.f, 0.f, 0.f, 0.f};
;     bf16x8 At[4][2], B0[2][2], B1[2][2];
;     const char* cA = (const char*)g.A + (size_t)rowstart(cur.pm) * rstepA + (size_t)cur.pn * gstepA; const char* cB = (const char*)g.Bt + (size_t)cur.pn * tstepB;
;     PG8_STAGE(PG8_SB(0, 0), cB, voffB); PG8_STAGE(PG8_SB(0, 1), cB + hstepB, voffB); PG8_STAGE(PG8_SA(0, 0), cA, voffA); PG8_STAGE(PG8_SA(0, 1), cA + hstepA, voffA);
;     if (wr == 1) PG8_BAR;
;     PG8_WAIT_V(2); PG8_BAR;
;     PG8_STAGE(PG8_SB(1, 0), cB + kstep, voffB); PG8_STAGE(PG8_SA(1, 0), cA + kstep, voffA); PG8_STAGE(PG8_SB(1, 1), cB + hstepB + kstep, voffB);
;     PG8_WAIT_V(6); PG8_BAR;
.LBB0_875:
	s_lshl_b32 s1, s1, 5
	s_mov_b64 s[12:13], 0x80
	s_and_b32 s1, s1, 0x60
	s_add_i32 m0, s46, 0x18000
	v_lshl_add_u64 v[6:7], v[6:7], 0, s[12:13]
	s_lshl_b32 s5, s0, 6
	s_lshl_b32 s7, s0, 13
	s_lshl_b32 s16, s1, 7
	s_waitcnt vmcnt(2)
	s_barrier
	global_load_lds_dwordx4 v[6:7], off
	v_lshl_add_u64 v[4:5], v[4:5], 0, s[12:13]
	s_add_i32 m0, s46, 0x1a000
	s_add_i32 s51, s46, 0x8000
	s_add_i32 s52, s46, 0xa000
	global_load_lds_dwordx4 v[4:5], off
	v_lshl_add_u64 v[0:1], v[0:1], 0, s[12:13]
	s_mov_b32 m0, s51
	s_add_u32 s14, s28, 0x40080
	global_load_lds_dwordx4 v[0:1], off
	v_lshl_add_u64 v[0:1], v[2:3], 0, s[12:13]
	s_mov_b32 m0, s52
	s_addc_u32 s15, s29, 0
	global_load_lds_dwordx4 v[0:1], off
	s_add_i32 m0, s46, 0x1c000
	v_lshl_add_u64 v[0:1], s[14:15], 0, v[130:131]
	global_load_lds_dwordx4 v[0:1], off
	v_lshl_add_u64 v[0:1], s[14:15], 0, v[134:135]
	s_add_i32 m0, s46, 0x1e000
	s_cmpk_lt_u32 s4, 0x100
	global_load_lds_dwordx4 v[0:1], off
	v_and_b32_e32 v0, 15, v163
	v_lshlrev_b32_e32 v1, 1, v11
	v_lshlrev_b32_e32 v3, 2, v0
	v_lshl_or_b32 v2, v0, 6, v1
	v_and_b32_e32 v4, 32, v3
	v_bitop3_b32 v2, v2, s7, v4 bitop3:0xde
	v_lshlrev_b32_e32 v4, 6, v163
	s_movk_i32 s7, 0x3c0
	v_and_or_b32 v1, v4, s7, v1
	v_lshlrev_b32_e32 v4, 2, v163
	v_and_b32_e32 v4, 32, v4
	v_or3_b32 v150, s5, v0, 16
	v_lshlrev_b32_e32 v0, 8, v163
	v_bitop3_b32 v149, s16, v1, v4 bitop3:0xf6
	v_and_b32_e32 v0, 0x38000, v0
	v_lshlrev_b32_e32 v1, 11, v10
	v_or3_b32 v0, v8, v0, v1
	s_cselect_b64 s[14:15], -1, 0
	s_lshl_b32 s0, s0, 8
	v_add_u32_e32 v136, v0, v9
	v_lshlrev_b32_e32 v0, 4, v12
	s_waitcnt vmcnt(6)
	s_add_i32 s0, s0, 0
	v_and_b32_e32 v0, 0x78000, v0
	s_add_i32 s0, s0, 0x20000
	v_or3_b32 v0, v8, v0, v1
	s_add_i32 s54, 0, 0x10000
	s_add_i32 s55, 0, 0x14000
	v_add_u32_e32 v151, s0, v3
	v_or_b32_e32 v152, s1, v11
	v_mov_b32_e32 v137, v131
	v_add_u32_e32 v138, v0, v9
	v_mov_b32_e32 v139, v131
	v_mov_b64_e32 v[140:141], 0xb00
	v_mov_b64_e32 v[142:143], 0xaff
	s_movk_i32 s53, 0x161
	v_add_u32_e32 v153, s54, v149
	v_add_u32_e32 v154, s55, v149
	v_add_u32_e32 v155, 0, v2
	v_mov_b32_e32 v156, 0x358637bd
	s_mov_b32 s56, 0xf800000
	v_mov_b32_e32 v157, 0x260
	s_movk_i32 s57, 0x1600
	s_barrier
	s_branch .LBB0_878
	s_nop 0
	s_nop 0
	s_nop 0
	s_nop 0
	s_nop 0
	s_nop 0
	s_nop 0
	s_nop 0

; template <class Epi>
; __device__ __forceinline__ void gemm_phase(LAS unsigned char* lds, const Gemm g, const StaticOrder& S, const Epi& E) {
;     ...
;         const char* nA = has_next ? (const char*)g.A + (size_t)rowstart(nxt.pm) * rstepA + (size_t)nxt.pn * gstepA : cA; const char* nB = has_next ? (const char*)g.Bt + (size_t)nxt.pn * tstepB : cB;
;         for (int t = 0; t < nt; t += 2) {
;             const bool last = (t == nt - 2);
;             const char* a1 = cA + (size_t)(t + 1) * kstep;
;             const char* a2 = last ? nA : cA + (size_t)(t + 2) * kstep; const char* b2 = last ? nB : cB + (size_t)(t + 2) * kstep;
;     ...
; #pragma unroll
;         for (int a = 0; a < 2; ++a)
; #pragma unroll
;             for (int b = 0; b < 2; ++b)
; #pragma unroll
;                 for (int m = 0; m < 4; ++m)
; #pragma unroll
;                     for (int n = 0; n < 2; ++n) acc[a][b][m][n] = (f32x4){0.f, 0.f, 0.f, 0.f};
.LBB0_882:
	s_ashr_i32 s17, s16, 31
	s_lshl_b64 s[26:27], s[16:17], 19
	s_add_u32 s26, s38, s26
	s_addc_u32 s27, s39, s27
	s_and_b64 s[0:1], s[0:1], exec
	s_cselect_b32 s7, s27, s29
	s_cselect_b32 s17, s26, s28
	s_add_u32 s0, s36, 0x40080
	s_addc_u32 s1, s37, 0
	s_add_u32 s60, s28, 0x100
	v_mov_b32_e32 v0, 0
	s_addc_u32 s61, s29, 0
	s_mov_b32 s62, -2
	v_mov_b32_e32 v1, v0
	v_mov_b32_e32 v2, v0
	v_mov_b32_e32 v3, v0
	v_mov_b32_e32 v4, v0
	v_mov_b32_e32 v5, v0
	v_mov_b32_e32 v6, v0
	v_mov_b32_e32 v7, v0
	v_mov_b32_e32 v16, v0
	v_mov_b32_e32 v17, v0
	v_mov_b32_e32 v18, v0
	v_mov_b32_e32 v19, v0
	v_mov_b32_e32 v20, v0
	v_mov_b32_e32 v21, v0
	v_mov_b32_e32 v22, v0
	v_mov_b32_e32 v23, v0
	v_mov_b32_e32 v32, v0
	v_mov_b32_e32 v33, v0
	v_mov_b32_e32 v34, v0
	v_mov_b32_e32 v35, v0
	v_mov_b32_e32 v36, v0
	v_mov_b32_e32 v37, v0
	v_mov_b32_e32 v38, v0
	v_mov_b32_e32 v39, v0
	v_mov_b32_e32 v48, v0
	v_mov_b32_e32 v49, v0
	v_mov_b32_e32 v50, v0
	v_mov_b32_e32 v51, v0
	v_mov_b32_e32 v52, v0
	v_mov_b32_e32 v53, v0
	v_mov_b32_e32 v54, v0
	v_mov_b32_e32 v55, v0
	v_mov_b32_e32 v8, v0
	v_mov_b32_e32 v9, v0
	v_mov_b32_e32 v10, v0
	v_mov_b32_e32 v11, v0
	v_mov_b32_e32 v12, v0
	v_mov_b32_e32 v13, v0
	v_mov_b32_e32 v14, v0
	v_mov_b32_e32 v15, v0
	v_mov_b32_e32 v24, v0
	v_mov_b32_e32 v25, v0
	v_mov_b32_e32 v26, v0
	v_mov_b32_e32 v27, v0
	v_mov_b32_e32 v28, v0
	v_mov_b32_e32 v29, v0
	v_mov_b32_e32 v30, v0
	v_mov_b32_e32 v31, v0
	v_mov_b32_e32 v40, v0
	v_mov_b32_e32 v41, v0
	v_mov_b32_e32 v42, v0
	v_mov_b32_e32 v43, v0
	v_mov_b32_e32 v44, v0
	v_mov_b32_e32 v45, v0
	v_mov_b32_e32 v46, v0
	v_mov_b32_e32 v47, v0
	v_mov_b32_e32 v56, v0
	v_mov_b32_e32 v57, v0
	v_mov_b32_e32 v58, v0
	v_mov_b32_e32 v59, v0
	v_mov_b32_e32 v60, v0
	v_mov_b32_e32 v61, v0
	v_mov_b32_e32 v62, v0
	v_mov_b32_e32 v63, v0
	v_mov_b32_e32 v64, v0
	v_mov_b32_e32 v65, v0
	v_mov_b32_e32 v66, v0
	v_mov_b32_e32 v67, v0
	v_mov_b32_e32 v68, v0
	v_mov_b32_e32 v69, v0
	v_mov_b32_e32 v70, v0
	v_mov_b32_e32 v71, v0
	v_mov_b32_e32 v80, v0
	v_mov_b32_e32 v81, v0
	v_mov_b32_e32 v82, v0
	v_mov_b32_e32 v83, v0
	v_mov_b32_e32 v84, v0
	v_mov_b32_e32 v85, v0
	v_mov_b32_e32 v86, v0
	v_mov_b32_e32 v87, v0
	v_mov_b32_e32 v96, v0
	v_mov_b32_e32 v97, v0
	v_mov_b32_e32 v98, v0
	v_mov_b32_e32 v99, v0
	v_mov_b32_e32 v100, v0
	v_mov_b32_e32 v101, v0
	v_mov_b32_e32 v102, v0
	v_mov_b32_e32 v103, v0
	v_mov_b32_e32 v112, v0
	v_mov_b32_e32 v113, v0
	v_mov_b32_e32 v114, v0
	v_mov_b32_e32 v115, v0
	v_mov_b32_e32 v116, v0
	v_mov_b32_e32 v117, v0
	v_mov_b32_e32 v118, v0
	v_mov_b32_e32 v119, v0
	v_mov_b32_e32 v72, v0
	v_mov_b32_e32 v73, v0
	v_mov_b32_e32 v74, v0
	v_mov_b32_e32 v75, v0
	v_mov_b32_e32 v76, v0
	v_mov_b32_e32 v77, v0
	v_mov_b32_e32 v78, v0
	v_mov_b32_e32 v79, v0
	v_mov_b32_e32 v88, v0
	v_mov_b32_e32 v89, v0
	v_mov_b32_e32 v90, v0
	v_mov_b32_e32 v91, v0
	v_mov_b32_e32 v92, v0
	v_mov_b32_e32 v93, v0
	v_mov_b32_e32 v94, v0
	v_mov_b32_e32 v95, v0
	v_mov_b32_e32 v104, v0
	v_mov_b32_e32 v105, v0
	v_mov_b32_e32 v106, v0
	v_mov_b32_e32 v107, v0
	v_mov_b32_e32 v108, v0
	v_mov_b32_e32 v109, v0
	v_mov_b32_e32 v110, v0
	v_mov_b32_e32 v111, v0
	v_mov_b32_e32 v120, v0
	v_mov_b32_e32 v121, v0
	v_mov_b32_e32 v122, v0
	v_mov_b32_e32 v123, v0
	v_mov_b32_e32 v124, v0
	v_mov_b32_e32 v125, v0
	v_mov_b32_e32 v126, v0
	v_mov_b32_e32 v127, v0
	s_nop 0
	s_nop 0
	s_nop 0
	s_nop 0
	s_nop 0
	s_nop 0
	s_nop 0
	s_nop 0
